# v83 with the early L2 writeback issued by the 4th-from-last arriver
# speedup vs baseline: 1.0034x; 1.0034x over previous
.LBB0_182:
	s_or_b64 exec, exec, s[12:13]
	v_cvt_f32_u32_e32 v4, v2
	s_waitcnt vmcnt(0)
	v_readfirstlane_b32 s10, v3
	v_sub_u32_e32 v3, 0, v2
	v_rcp_iflag_f32_e32 v4, v4
	v_add_u32_e32 v5, s10, v1
	v_mul_f32_e32 v4, 0x4f7ffffe, v4
	v_cvt_u32_f32_e32 v4, v4
	v_mul_lo_u32 v1, v3, v4
	v_mul_hi_u32 v1, v4, v1
	v_add_u32_e32 v1, v4, v1
	v_mul_hi_u32 v1, v5, v1
	v_mul_lo_u32 v3, v1, v2
	v_sub_u32_e32 v3, v5, v3
	v_add_u32_e32 v4, 1, v1
	v_cmp_ge_u32_e32 vcc, v3, v2
	s_nop 1
	v_cndmask_b32_e32 v1, v1, v4, vcc
	v_sub_u32_e32 v4, v3, v2
	v_cndmask_b32_e32 v3, v3, v4, vcc
	v_add_u32_e32 v4, 1, v1
	v_cmp_ge_u32_e32 vcc, v3, v2
	v_add_u32_e32 v3, 1, v5
	s_nop 0
	v_cndmask_b32_e32 v1, v1, v4, vcc
	v_mul_lo_u32 v4, v2, v1
	v_add_u32_e32 v2, v4, v2
	v_cmp_ne_u32_e32 vcc, v3, v2
	s_and_saveexec_b64 s[10:11], vcc
	s_xor_b64 s[10:11], exec, s[10:11]
	s_cbranch_execz .LBB0_196
	v_add_u32_e32 v0, 4, v5
	v_cmp_eq_u32_e32 vcc, v0, v2
	s_and_b64 vcc, exec, vcc
	s_cbranch_vccz .Lfirstwb_skip_0
	buffer_wbl2 sc1

.LBB0_1296:
	s_or_b64 exec, exec, s[16:17]
	v_cvt_f32_u32_e32 v4, v2
	s_waitcnt vmcnt(0)
	v_readfirstlane_b32 s12, v3
	v_sub_u32_e32 v3, 0, v2
	v_rcp_iflag_f32_e32 v4, v4
	v_add_u32_e32 v5, s12, v1
	v_mul_f32_e32 v4, 0x4f7ffffe, v4
	v_cvt_u32_f32_e32 v4, v4
	v_mul_lo_u32 v1, v3, v4
	v_mul_hi_u32 v1, v4, v1
	v_add_u32_e32 v1, v4, v1
	v_mul_hi_u32 v1, v5, v1
	v_mul_lo_u32 v3, v1, v2
	v_sub_u32_e32 v3, v5, v3
	v_add_u32_e32 v4, 1, v1
	v_cmp_ge_u32_e32 vcc, v3, v2
	s_nop 1
	v_cndmask_b32_e32 v1, v1, v4, vcc
	v_sub_u32_e32 v4, v3, v2
	v_cndmask_b32_e32 v3, v3, v4, vcc
	v_add_u32_e32 v4, 1, v1
	v_cmp_ge_u32_e32 vcc, v3, v2
	v_add_u32_e32 v3, 1, v5
	s_nop 0
	v_cndmask_b32_e32 v1, v1, v4, vcc
	v_mul_lo_u32 v4, v2, v1
	v_add_u32_e32 v2, v4, v2
	v_cmp_ne_u32_e32 vcc, v3, v2
	s_and_saveexec_b64 s[12:13], vcc
	s_xor_b64 s[12:13], exec, s[12:13]
	s_cbranch_execz .LBB0_1310
	v_add_u32_e32 v0, 4, v5
	v_cmp_eq_u32_e32 vcc, v0, v2
	s_and_b64 vcc, exec, vcc
	s_cbranch_vccz .Lfirstwb_skip_3
	buffer_wbl2 sc1

.LBB0_1953:
	s_or_b64 exec, exec, s[14:15]
	v_cvt_f32_u32_e32 v4, v2
	s_waitcnt vmcnt(0)
	v_readfirstlane_b32 s12, v3
	v_sub_u32_e32 v3, 0, v2
	v_rcp_iflag_f32_e32 v4, v4
	v_add_u32_e32 v5, s12, v1
	v_mul_f32_e32 v4, 0x4f7ffffe, v4
	v_cvt_u32_f32_e32 v4, v4
	v_mul_lo_u32 v1, v3, v4
	v_mul_hi_u32 v1, v4, v1
	v_add_u32_e32 v1, v4, v1
	v_mul_hi_u32 v1, v5, v1
	v_mul_lo_u32 v3, v1, v2
	v_sub_u32_e32 v3, v5, v3
	v_add_u32_e32 v4, 1, v1
	v_cmp_ge_u32_e32 vcc, v3, v2
	s_nop 1
	v_cndmask_b32_e32 v1, v1, v4, vcc
	v_sub_u32_e32 v4, v3, v2
	v_cndmask_b32_e32 v3, v3, v4, vcc
	v_add_u32_e32 v4, 1, v1
	v_cmp_ge_u32_e32 vcc, v3, v2
	v_add_u32_e32 v3, 1, v5
	s_nop 0
	v_cndmask_b32_e32 v1, v1, v4, vcc
	v_mul_lo_u32 v4, v2, v1
	v_add_u32_e32 v2, v4, v2
	v_cmp_ne_u32_e32 vcc, v3, v2
	s_and_saveexec_b64 s[12:13], vcc
	s_xor_b64 s[12:13], exec, s[12:13]
	s_cbranch_execz .LBB0_1967
	v_add_u32_e32 v0, 4, v5
	v_cmp_eq_u32_e32 vcc, v0, v2
	s_and_b64 vcc, exec, vcc
	s_cbranch_vccz .Lfirstwb_skip_4
	buffer_wbl2 sc1
